# attention items: epilogue gain vectors requested before the tile loop (rebalanced static mix)
# speedup vs baseline: 1.0123x; 1.0050x over previous
.LBB0_114:
	v_sub_f32_e32 v92, v92, v163
	v_sub_f32_e32 v93, v93, v163
	v_exp_f32_e32 v92, v92
	v_exp_f32_e32 v93, v93
	v_sub_f32_e32 v88, v88, v163
	v_sub_f32_e32 v94, v94, v163
	v_exp_f32_e32 v105, v88
	v_sub_f32_e32 v88, v89, v163
	v_exp_f32_e32 v94, v94
	v_sub_f32_e32 v95, v95, v163
	v_exp_f32_e32 v106, v88
	v_sub_f32_e32 v88, v90, v163
	v_exp_f32_e32 v95, v95
	v_exp_f32_e32 v107, v88
	v_sub_f32_e32 v88, v91, v163
	v_exp_f32_e32 v108, v88
	v_cvt_pk_bf16_f32 v88, v92, v93
	v_add_f32_e32 v92, 0, v92
	v_add_f32_e32 v92, v93, v92
	v_add_f32_e32 v92, v94, v92
	v_sub_f32_e32 v72, v100, v163
	v_add_f32_e32 v92, v95, v92
	v_exp_f32_e32 v100, v72
	v_sub_f32_e32 v72, v101, v163
	v_add_f32_e32 v92, v105, v92
	v_exp_f32_e32 v101, v72
	v_sub_f32_e32 v72, v102, v163
	v_add_f32_e32 v92, v106, v92
	v_exp_f32_e32 v102, v72
	v_sub_f32_e32 v72, v103, v163
	v_add_f32_e32 v92, v107, v92
	v_exp_f32_e32 v103, v72
	v_sub_f32_e32 v72, v96, v163
	v_add_f32_e32 v92, v108, v92
	v_exp_f32_e32 v96, v72
	v_sub_f32_e32 v72, v97, v163
	v_add_f32_e32 v92, v100, v92
	v_exp_f32_e32 v97, v72
	v_sub_f32_e32 v72, v98, v163
	v_add_f32_e32 v92, v101, v92
	v_exp_f32_e32 v98, v72
	v_sub_f32_e32 v72, v99, v163
	v_add_f32_e32 v92, v102, v92
	s_waitcnt lgkmcnt(0)
	v_add_f32_e32 v3, v3, v104
	v_add_f32_e32 v0, v0, v2
	v_exp_f32_e32 v99, v72
	v_add_f32_e32 v92, v103, v92
	v_mul_f32_e32 v3, 0x3fb8aa3b, v3
	v_mul_f32_e32 v0, 0x3fb8aa3b, v0
	v_add_f32_e32 v92, v96, v92
	v_exp_f32_e32 v3, v3
	v_exp_f32_e32 v0, v0
	v_add_f32_e32 v92, v97, v92
	v_add_f32_e32 v2, v98, v92
	v_add_f32_e32 v2, v99, v2
	v_cvt_pk_bf16_f32 v91, v107, v108
	v_add_f32_e32 v108, v141, v2
	v_sub_f32_e32 v2, v3, v0
	v_sub_f32_e32 v0, v84, v161
	v_exp_f32_e32 v0, v0
	v_sub_f32_e32 v3, v85, v161
	v_exp_f32_e32 v3, v3
	v_sub_f32_e32 v84, v86, v161
	v_exp_f32_e32 v84, v84
	v_sub_f32_e32 v85, v87, v161
	v_exp_f32_e32 v85, v85
	v_sub_f32_e32 v80, v80, v161
	v_add_f32_e32 v86, 0, v0
	v_exp_f32_e32 v80, v80
	v_sub_f32_e32 v81, v81, v161
	v_add_f32_e32 v86, v3, v86
	v_exp_f32_e32 v81, v81
	v_sub_f32_e32 v82, v82, v161
	v_add_f32_e32 v86, v84, v86
	v_exp_f32_e32 v82, v82
	v_sub_f32_e32 v83, v83, v161
	v_add_f32_e32 v86, v85, v86
	v_exp_f32_e32 v83, v83
	v_sub_f32_e32 v76, v76, v161
	v_add_f32_e32 v86, v80, v86
	v_exp_f32_e32 v76, v76
	v_sub_f32_e32 v77, v77, v161
	v_add_f32_e32 v86, v81, v86
	v_exp_f32_e32 v77, v77
	v_sub_f32_e32 v78, v78, v161
	v_add_f32_e32 v86, v82, v86
	v_exp_f32_e32 v78, v78
	v_sub_f32_e32 v79, v79, v161
	v_add_f32_e32 v86, v83, v86
	v_exp_f32_e32 v79, v79
	v_sub_f32_e32 v68, v68, v161
	v_add_f32_e32 v86, v76, v86
	v_exp_f32_e32 v87, v68
	v_sub_f32_e32 v68, v69, v161
	v_add_f32_e32 v86, v77, v86
	v_exp_f32_e32 v92, v68
	v_sub_f32_e32 v68, v70, v161
	v_add_f32_e32 v86, v78, v86
	v_exp_f32_e32 v93, v68
	v_sub_f32_e32 v68, v71, v161
	v_cvt_pk_bf16_f32 v89, v94, v95
	v_add_f32_e32 v86, v79, v86
	v_exp_f32_e32 v94, v68
	v_add_f32_e32 v68, v87, v86
	v_add_f32_e32 v68, v92, v68
	v_add_f32_e32 v68, v93, v68
	v_add_f32_e32 v68, v94, v68
	v_add_f32_e32 v109, v140, v68
	v_cvt_pk_bf16_f32 v68, v0, v3
	v_cvt_pk_bf16_f32 v70, v80, v81
	v_add_u32_e32 v0, 0x8000, v117
	ds_read_b64 v[80:81], v0 offset:0
	v_cvt_pk_bf16_f32 v71, v82, v83
	v_add_u32_e32 v3, 0x8000, v137
	ds_read_b64 v[82:83], v3 offset:0
	v_cvt_pk_bf16_f32 v69, v84, v85
	v_add_u32_e32 v110, 0x8000, v138
	ds_read_b64 v[84:85], v110 offset:0
	v_cvt_pk_bf16_f32 v76, v76, v77
	v_cvt_pk_bf16_f32 v77, v78, v79
	v_cvt_pk_bf16_f32 v78, v87, v92
	v_add_u32_e32 v111, 0x8000, v139
	ds_read_b64 v[86:87], v111 offset:0
	v_cvt_pk_bf16_f32 v79, v93, v94
	ds_read_b64 v[92:93], v0 offset:2048
	ds_read_b64 v[94:95], v3 offset:2048
	v_cvt_pk_bf16_f32 v74, v96, v97
	ds_read_b64 v[96:97], v110 offset:2048
	v_cvt_pk_bf16_f32 v75, v98, v99
	ds_read_b64 v[98:99], v111 offset:2048
	v_cvt_pk_bf16_f32 v72, v100, v101
	ds_read_b64 v[100:101], v0 offset:4096
	v_cvt_pk_bf16_f32 v73, v102, v103
	ds_read_b64 v[102:103], v3 offset:4096
	v_cvt_pk_bf16_f32 v90, v105, v106
	ds_read_b64 v[104:105], v110 offset:4096
	ds_read_b64 v[106:107], v111 offset:4096
	s_waitcnt lgkmcnt(8)
	s_nop 1
	v_mfma_f32_16x16x32_bf16 v[64:67], v[80:83], v[88:91], v[64:67]
	v_mfma_f32_16x16x32_bf16 v[80:83], v[80:83], v[68:71], v[60:63]
	v_mfma_f32_16x16x32_bf16 v[60:63], v[84:87], v[72:75], v[64:67]
	v_mfma_f32_16x16x32_bf16 v[64:67], v[84:87], v[76:79], v[80:83]
	ds_read_b64 v[80:81], v0 offset:6144
	ds_read_b64 v[82:83], v3 offset:6144
	ds_read_b64 v[84:85], v110 offset:6144
	ds_read_b64 v[86:87], v111 offset:6144
	s_waitcnt lgkmcnt(8)
	v_mfma_f32_16x16x32_bf16 v[56:59], v[92:95], v[88:91], v[56:59]
	v_mfma_f32_16x16x32_bf16 v[92:95], v[92:95], v[68:71], v[52:55]
	v_mfma_f32_16x16x32_bf16 v[52:55], v[96:99], v[72:75], v[56:59]
	v_mfma_f32_16x16x32_bf16 v[56:59], v[96:99], v[76:79], v[92:95]
	ds_read_b64 v[92:93], v0 offset:8192
	ds_read_b64 v[94:95], v3 offset:8192
	ds_read_b64 v[96:97], v110 offset:8192
	ds_read_b64 v[98:99], v111 offset:8192
	s_waitcnt lgkmcnt(8)
	v_mfma_f32_16x16x32_bf16 v[48:51], v[100:103], v[88:91], v[48:51]
	v_mfma_f32_16x16x32_bf16 v[100:103], v[100:103], v[68:71], v[44:47]
	v_mfma_f32_16x16x32_bf16 v[44:47], v[104:107], v[72:75], v[48:51]
	v_mfma_f32_16x16x32_bf16 v[48:51], v[104:107], v[76:79], v[100:103]
	ds_read_b64 v[100:101], v0 offset:10240
	ds_read_b64 v[102:103], v3 offset:10240
	ds_read_b64 v[104:105], v110 offset:10240
	ds_read_b64 v[106:107], v111 offset:10240
	s_waitcnt lgkmcnt(8)
	v_mfma_f32_16x16x32_bf16 v[40:43], v[80:83], v[88:91], v[40:43]
	v_mfma_f32_16x16x32_bf16 v[80:83], v[80:83], v[68:71], v[36:39]
	v_mfma_f32_16x16x32_bf16 v[36:39], v[84:87], v[72:75], v[40:43]
	v_mfma_f32_16x16x32_bf16 v[40:43], v[84:87], v[76:79], v[80:83]
	ds_read_b64 v[80:81], v0 offset:12288
	ds_read_b64 v[82:83], v3 offset:12288
	ds_read_b64 v[84:85], v110 offset:12288
	ds_read_b64 v[86:87], v111 offset:12288
	s_waitcnt lgkmcnt(8)
	v_mfma_f32_16x16x32_bf16 v[32:35], v[92:95], v[88:91], v[32:35]
	v_mfma_f32_16x16x32_bf16 v[92:95], v[92:95], v[68:71], v[28:31]
	v_mfma_f32_16x16x32_bf16 v[28:31], v[96:99], v[72:75], v[32:35]
	v_mfma_f32_16x16x32_bf16 v[32:35], v[96:99], v[76:79], v[92:95]
	ds_read_b64 v[92:93], v0 offset:14336
	ds_read_b64 v[94:95], v3 offset:14336
	ds_read_b64 v[96:97], v110 offset:14336
	ds_read_b64 v[98:99], v111 offset:14336
	s_waitcnt lgkmcnt(8)
	v_mfma_f32_16x16x32_bf16 v[24:27], v[100:103], v[88:91], v[24:27]
	v_mfma_f32_16x16x32_bf16 v[100:103], v[100:103], v[68:71], v[16:19]
	v_mfma_f32_16x16x32_bf16 v[16:19], v[104:107], v[72:75], v[24:27]
	v_mfma_f32_16x16x32_bf16 v[100:103], v[104:107], v[76:79], v[100:103]
	s_waitcnt lgkmcnt(4)
	v_mfma_f32_16x16x32_bf16 v[20:23], v[80:83], v[88:91], v[20:23]
	v_mfma_f32_16x16x32_bf16 v[24:27], v[80:83], v[68:71], v[8:11]
	v_mfma_f32_16x16x32_bf16 v[8:11], v[84:87], v[72:75], v[20:23]
	v_mfma_f32_16x16x32_bf16 v[80:83], v[84:87], v[76:79], v[24:27]
	s_waitcnt lgkmcnt(0)
	v_mfma_f32_16x16x32_bf16 v[12:15], v[92:95], v[88:91], v[12:15]
	v_mfma_f32_16x16x32_bf16 v[4:7], v[92:95], v[68:71], v[4:7]
	v_mfma_f32_16x16x32_bf16 v[68:71], v[96:99], v[72:75], v[12:15]
	v_mfma_f32_16x16x32_bf16 v[72:75], v[96:99], v[76:79], v[4:7]
	ds_bpermute_b32 v0, v136, v108
	s_waitcnt lgkmcnt(0)
	v_add_f32_e32 v0, v108, v0
	ds_bpermute_b32 v3, v135, v0
	s_waitcnt lgkmcnt(0)
	v_add_f32_e32 v0, v0, v3
	ds_bpermute_b32 v3, v136, v109
	v_div_scale_f32 v4, s[6:7], v0, v0, 1.0
	v_rcp_f32_e32 v5, v4
	s_waitcnt lgkmcnt(0)
	v_add_f32_e32 v3, v109, v3
	ds_bpermute_b32 v117, v135, v3
	v_fma_f32 v6, -v4, v5, 1.0
	v_fmac_f32_e32 v5, v6, v5
	v_div_scale_f32 v6, vcc, 1.0, v0, 1.0
	v_mul_f32_e32 v7, v6, v5
	v_fma_f32 v12, -v4, v7, v6
	v_fmac_f32_e32 v7, v12, v5
	v_fma_f32 v4, -v4, v7, v6
	s_waitcnt lgkmcnt(0)
	v_pk_add_f32 v[2:3], v[116:117], v[2:3]
	v_div_fmas_f32 v4, v4, v5, v7
	v_div_fixup_f32 v0, v4, v0, 1.0
	v_div_scale_f32 v4, s[6:7], v3, v3, v2
	v_rcp_f32_e32 v5, v4
	v_readlane_b32 s6, v217, 30
	v_readlane_b32 s7, v217, 31
	v_fma_f32 v6, -v4, v5, 1.0
	v_fmac_f32_e32 v5, v6, v5
	v_div_scale_f32 v6, vcc, v2, v3, v2
	v_mul_f32_e32 v7, v6, v5
	v_fma_f32 v12, -v4, v7, v6
	v_fmac_f32_e32 v7, v12, v5
	v_fma_f32 v4, -v4, v7, v6
	v_div_fmas_f32 v4, v4, v5, v7
	v_div_fixup_f32 v2, v4, v3, v2
	v_pk_mul_f32 v[4:5], v[64:65], v[2:3] op_sel_hi:[1,0]
	v_pk_mul_f32 v[6:7], v[66:67], v[2:3] op_sel_hi:[1,0]
	v_pk_fma_f32 v[12:13], v[60:61], v[0:1], v[4:5] op_sel_hi:[1,0,1] neg_lo:[0,0,1] neg_hi:[0,0,1]
	v_pk_fma_f32 v[6:7], v[62:63], v[0:1], v[6:7] op_sel_hi:[1,0,1] neg_lo:[0,0,1] neg_hi:[0,0,1]
	v_mul_f32_e32 v3, v13, v13
	v_fmac_f32_e32 v3, v12, v12
	v_fmac_f32_e32 v3, v6, v6
	v_fmac_f32_e32 v3, v7, v7
	v_pk_mul_f32 v[4:5], v[56:57], v[2:3] op_sel_hi:[1,0]
	v_pk_mul_f32 v[14:15], v[58:59], v[2:3] op_sel_hi:[1,0]
	v_pk_fma_f32 v[22:23], v[52:53], v[0:1], v[4:5] op_sel_hi:[1,0,1] neg_lo:[0,0,1] neg_hi:[0,0,1]
	v_pk_fma_f32 v[14:15], v[54:55], v[0:1], v[14:15] op_sel_hi:[1,0,1] neg_lo:[0,0,1] neg_hi:[0,0,1]
	v_mul_f32_e32 v4, v23, v23
	v_fmac_f32_e32 v4, v22, v22
	v_fmac_f32_e32 v4, v14, v14
	v_fmac_f32_e32 v4, v15, v15
	v_add_f32_e32 v3, v3, v4
	v_pk_mul_f32 v[4:5], v[48:49], v[2:3] op_sel_hi:[1,0]
	v_pk_mul_f32 v[20:21], v[50:51], v[2:3] op_sel_hi:[1,0]
	v_pk_fma_f32 v[44:45], v[44:45], v[0:1], v[4:5] op_sel_hi:[1,0,1] neg_lo:[0,0,1] neg_hi:[0,0,1]
	v_pk_mul_f32 v[4:5], v[40:41], v[2:3] op_sel_hi:[1,0]
	v_pk_fma_f32 v[26:27], v[46:47], v[0:1], v[20:21] op_sel_hi:[1,0,1] neg_lo:[0,0,1] neg_hi:[0,0,1]
	v_pk_fma_f32 v[24:25], v[36:37], v[0:1], v[4:5] op_sel_hi:[1,0,1] neg_lo:[0,0,1] neg_hi:[0,0,1]
	v_pk_mul_f32 v[20:21], v[42:43], v[2:3] op_sel_hi:[1,0]
	v_mov_b32_e32 v36, v25
	v_mov_b32_e32 v37, v45
	v_pk_fma_f32 v[20:21], v[38:39], v[0:1], v[20:21] op_sel_hi:[1,0,1] neg_lo:[0,0,1] neg_hi:[0,0,1]
	v_mov_b32_e32 v4, v24
	v_mov_b32_e32 v5, v44
	v_pk_mul_f32 v[36:37], v[36:37], v[36:37]
	s_nop 0
	v_pk_fma_f32 v[4:5], v[4:5], v[4:5], v[36:37]
	v_mov_b32_e32 v36, v20
	v_mov_b32_e32 v37, v26
	v_pk_fma_f32 v[4:5], v[36:37], v[36:37], v[4:5]
	v_mov_b32_e32 v36, v21
	v_mov_b32_e32 v37, v27
	v_pk_fma_f32 v[4:5], v[36:37], v[36:37], v[4:5]
	v_lshlrev_b32_e32 v37, 4, v134
	v_add_f32_e32 v3, v5, v3
	v_add_f32_e32 v3, v4, v3
	v_pk_mul_f32 v[4:5], v[32:33], v[2:3] op_sel_hi:[1,0]
	v_pk_mul_f32 v[32:33], v[34:35], v[2:3] op_sel_hi:[1,0]
	v_pk_fma_f32 v[34:35], v[28:29], v[0:1], v[4:5] op_sel_hi:[1,0,1] neg_lo:[0,0,1] neg_hi:[0,0,1]
	v_pk_mul_f32 v[4:5], v[100:101], v[2:3] op_sel_hi:[1,0]
	v_pk_mul_f32 v[28:29], v[102:103], v[2:3] op_sel_hi:[1,0]
	v_pk_fma_f32 v[16:17], v[16:17], v[0:1], v[4:5] op_sel_hi:[1,0,1] neg_lo:[0,0,1] neg_hi:[0,0,1]
	v_pk_fma_f32 v[18:19], v[18:19], v[0:1], v[28:29] op_sel_hi:[1,0,1] neg_lo:[0,0,1] neg_hi:[0,0,1]
	v_mov_b32_e32 v28, v17
	v_mov_b32_e32 v29, v35
	v_pk_fma_f32 v[30:31], v[30:31], v[0:1], v[32:33] op_sel_hi:[1,0,1] neg_lo:[0,0,1] neg_hi:[0,0,1]
	v_mov_b32_e32 v4, v16
	v_mov_b32_e32 v5, v34
	v_pk_mul_f32 v[28:29], v[28:29], v[28:29]
	s_nop 0
	v_pk_fma_f32 v[4:5], v[4:5], v[4:5], v[28:29]
	v_mov_b32_e32 v28, v18
	v_mov_b32_e32 v29, v30
	v_pk_fma_f32 v[4:5], v[28:29], v[28:29], v[4:5]
	v_mov_b32_e32 v28, v19
	v_mov_b32_e32 v29, v31
	v_pk_fma_f32 v[4:5], v[28:29], v[28:29], v[4:5]
	s_nop 0
	v_add_f32_e32 v3, v5, v3
	v_add_f32_e32 v36, v4, v3
	v_pk_mul_f32 v[4:5], v[80:81], v[2:3] op_sel_hi:[1,0]
	v_pk_mul_f32 v[28:29], v[82:83], v[2:3] op_sel_hi:[1,0]
	v_pk_fma_f32 v[32:33], v[8:9], v[0:1], v[4:5] op_sel_hi:[1,0,1] neg_lo:[0,0,1] neg_hi:[0,0,1]
	v_pk_mul_f32 v[4:5], v[72:73], v[2:3] op_sel_hi:[1,0]
	v_pk_fma_f32 v[28:29], v[10:11], v[0:1], v[28:29] op_sel_hi:[1,0,1] neg_lo:[0,0,1] neg_hi:[0,0,1]
	v_pk_fma_f32 v[10:11], v[68:69], v[0:1], v[4:5] op_sel_hi:[1,0,1] neg_lo:[0,0,1] neg_hi:[0,0,1]
	v_pk_mul_f32 v[2:3], v[74:75], v[2:3] op_sel_hi:[1,0]
	v_mov_b32_e32 v4, v11
	v_mov_b32_e32 v5, v33
	v_pk_fma_f32 v[8:9], v[70:71], v[0:1], v[2:3] op_sel_hi:[1,0,1] neg_lo:[0,0,1] neg_hi:[0,0,1]
	v_mov_b32_e32 v2, v10
	v_mov_b32_e32 v3, v32
	v_pk_mul_f32 v[4:5], v[4:5], v[4:5]
	s_nop 0
	v_pk_fma_f32 v[2:3], v[2:3], v[2:3], v[4:5]
	v_mov_b32_e32 v4, v8
	v_mov_b32_e32 v5, v28
	v_pk_fma_f32 v[2:3], v[4:5], v[4:5], v[2:3]
	v_mov_b32_e32 v4, v9
	v_mov_b32_e32 v5, v29
	v_pk_fma_f32 v[2:3], v[4:5], v[4:5], v[2:3]
	s_nop 0
	v_add_f32_e32 v0, v3, v36
	v_add_f32_e32 v0, v2, v0
	ds_bpermute_b32 v2, v136, v0
	s_waitcnt lgkmcnt(0)
	v_add_f32_e32 v0, v0, v2
	ds_bpermute_b32 v2, v135, v0
	s_waitcnt lgkmcnt(0)
	v_add_f32_e32 v0, v0, v2
	v_fmamk_f32 v0, v0, 0x3c000000, v144
	v_rsq_f32_e32 v0, v0
	v_lshl_add_u64 v[2:3], v[120:121], 1, s[6:7]
	v_mul_f32_e32 v36, v119, v0
	v_lshlrev_b32_e32 v0, 1, v118
	v_lshl_add_u64 v[2:3], v[2:3], 0, v[0:1]
	v_lshlrev_b32_e32 v0, 3, v134
	v_lshl_add_u64 v[38:39], v[2:3], 0, v[0:1]
	v_pk_mul_f32 v[12:13], v[12:13], v[36:37] op_sel_hi:[1,0]
	v_pk_mul_f32 v[6:7], v[6:7], v[36:37] op_sel_hi:[1,0]
	v_pk_mul_f32 v[8:9], v[8:9], v[36:37] op_sel_hi:[1,0]
	s_waitcnt vmcnt(0)
	v_pk_mul_f32 v[4:5], v[220:221], v[6:7]
	v_pk_mul_f32 v[2:3], v[218:219], v[12:13]
	v_pk_mul_f32 v[6:7], v[22:23], v[36:37] op_sel_hi:[1,0]
	v_cvt_pk_bf16_f32 v2, v2, v3
	v_cvt_pk_bf16_f32 v3, v4, v5
	global_store_dwordx2 v[38:39], v[2:3], off
	v_pk_mul_f32 v[12:13], v[14:15], v[36:37] op_sel_hi:[1,0]
	v_pk_mul_f32 v[2:3], v[222:223], v[6:7]
	v_pk_mul_f32 v[4:5], v[224:225], v[12:13]
	v_cvt_pk_bf16_f32 v2, v2, v3
	v_cvt_pk_bf16_f32 v3, v4, v5
	global_store_dwordx2 v[38:39], v[2:3], off offset:32
	v_pk_mul_f32 v[6:7], v[44:45], v[36:37] op_sel_hi:[1,0]
	v_pk_mul_f32 v[12:13], v[26:27], v[36:37] op_sel_hi:[1,0]
	v_pk_mul_f32 v[2:3], v[226:227], v[6:7]
	v_pk_mul_f32 v[4:5], v[228:229], v[12:13]
	v_cvt_pk_bf16_f32 v2, v2, v3
	v_cvt_pk_bf16_f32 v3, v4, v5
	global_store_dwordx2 v[38:39], v[2:3], off offset:64
	v_pk_mul_f32 v[6:7], v[24:25], v[36:37] op_sel_hi:[1,0]
	v_pk_mul_f32 v[12:13], v[20:21], v[36:37] op_sel_hi:[1,0]
	v_pk_mul_f32 v[2:3], v[230:231], v[6:7]
	v_pk_mul_f32 v[4:5], v[232:233], v[12:13]
	v_cvt_pk_bf16_f32 v2, v2, v3
	v_cvt_pk_bf16_f32 v3, v4, v5
	global_store_dwordx2 v[38:39], v[2:3], off offset:96
	v_pk_mul_f32 v[6:7], v[34:35], v[36:37] op_sel_hi:[1,0]
	v_pk_mul_f32 v[12:13], v[30:31], v[36:37] op_sel_hi:[1,0]
	v_pk_mul_f32 v[2:3], v[234:235], v[6:7]
	v_pk_mul_f32 v[4:5], v[236:237], v[12:13]
	v_cvt_pk_bf16_f32 v2, v2, v3
	v_cvt_pk_bf16_f32 v3, v4, v5
	global_store_dwordx2 v[38:39], v[2:3], off offset:128
	v_pk_mul_f32 v[6:7], v[16:17], v[36:37] op_sel_hi:[1,0]
	v_pk_mul_f32 v[12:13], v[18:19], v[36:37] op_sel_hi:[1,0]
	v_pk_mul_f32 v[2:3], v[238:239], v[6:7]
	v_pk_mul_f32 v[4:5], v[240:241], v[12:13]
	v_cvt_pk_bf16_f32 v2, v2, v3
	v_cvt_pk_bf16_f32 v3, v4, v5
	global_store_dwordx2 v[38:39], v[2:3], off offset:160
	v_pk_mul_f32 v[6:7], v[32:33], v[36:37] op_sel_hi:[1,0]
	v_pk_mul_f32 v[12:13], v[28:29], v[36:37] op_sel_hi:[1,0]
	v_pk_mul_f32 v[2:3], v[242:243], v[6:7]
	v_pk_mul_f32 v[4:5], v[244:245], v[12:13]
	v_cvt_pk_bf16_f32 v2, v2, v3
	v_cvt_pk_bf16_f32 v3, v4, v5
	global_store_dwordx2 v[38:39], v[2:3], off offset:192
	v_pk_mul_f32 v[6:7], v[10:11], v[36:37] op_sel_hi:[1,0]
	v_pk_mul_f32 v[4:5], v[248:249], v[8:9]
	v_pk_mul_f32 v[2:3], v[246:247], v[6:7]
	s_nop 0
	v_cvt_pk_bf16_f32 v2, v2, v3
	v_cvt_pk_bf16_f32 v3, v4, v5
	global_store_dwordx2 v[38:39], v[2:3], off offset:224

.LBB0_137:
	s_andn2_saveexec_b64 s[4:5], s[4:5]
	s_cbranch_execz .LBB0_151
	v_mov_b32_e32 v30, v142
	v_cmp_lt_i32_e32 vcc, v149, v148
	v_and_b32_e32 v4, 63, v30
	v_lshlrev_b32_e32 v4, 2, v4
	global_load_dword v28, v4, s[42:43]
	global_load_dword v29, v4, s[42:43] offset:256
	global_load_dword v31, v4, s[42:43] offset:512
	global_load_dword v32, v4, s[42:43] offset:768
	v_cndmask_b32_e32 v6, v147, v149, vcc
	v_cmp_lt_i32_e32 vcc, v150, v148
	v_add_u32_e32 v0, -16, v0
	v_lshlrev_b32_e32 v4, 7, v2
	v_cndmask_b32_e32 v7, v147, v150, vcc
	v_cmp_lt_i32_e32 vcc, v151, v148
	v_lshrrev_b32_e32 v10, 1, v0
	v_lshlrev_b32_e32 v118, 7, v3
	v_cndmask_b32_e32 v8, v147, v151, vcc
	v_cmp_lt_i32_e32 vcc, v152, v148
	v_and_b32_e32 v12, 0x80, v4
	v_lshlrev_b32_e32 v136, 2, v7
	v_cndmask_b32_e32 v9, v147, v152, vcc
	v_lshlrev_b32_e32 v34, 2, v9
	v_and_b32_e32 v35, 15, v30
	v_lshlrev_b32_e32 v7, 8, v10
	v_ashrrev_i32_e32 v9, 2, v30
	v_lshlrev_b32_e32 v0, 18, v10
	v_lshlrev_b32_e32 v135, 2, v6
	v_lshl_add_u32 v4, v10, 10, v118
	v_ashrrev_i32_e32 v6, 4, v30
	v_and_b32_e32 v13, -16, v9
	v_lshlrev_b64 v[10:11], 1, v[0:1]
	v_lshlrev_b32_e32 v0, 8, v3
	v_or3_b32 v3, v7, v12, v35
	v_xor_b32_e32 v19, v6, v30
	v_add_u32_e32 v18, v3, v13
	v_readlane_b32 s6, v217, 41
	v_lshlrev_b32_e32 v3, 4, v19
	v_ashrrev_i32_e32 v19, 31, v18
	v_readlane_b32 s8, v217, 45
	v_readlane_b32 s7, v217, 42
	v_lshlrev_b64 v[24:25], 11, v[18:19]
	v_readlane_b32 s9, v217, 46
	v_add_u32_e32 v36, 0x200, v30
	v_lshl_add_u64 v[14:15], s[6:7], 0, v[10:11]
	v_lshl_add_u64 v[24:25], s[8:9], 0, v[24:25]
	v_lshrrev_b32_e32 v37, 4, v30
	v_ashrrev_i32_e32 v12, 4, v36
	v_lshl_add_u64 v[14:15], v[14:15], 0, v[0:1]
	v_lshl_add_u64 v[24:25], v[24:25], 0, v[0:1]
	v_and_b32_e32 v0, 48, v30
	v_xor_b32_e32 v22, v37, v30
	v_ashrrev_i32_e32 v13, 31, v12
	v_lshl_add_u64 v[24:25], v[24:25], 0, v[0:1]
	v_and_b32_e32 v0, 0xf0, v3
	v_lshlrev_b32_e32 v40, 4, v22
	v_lshlrev_b64 v[22:23], 11, v[12:13]
	v_ashrrev_i32_e32 v7, 31, v6
	v_lshlrev_b64 v[20:21], 11, v[6:7]
	v_xor_b32_e32 v7, v12, v30
	v_lshlrev_b32_e32 v7, 4, v7
	v_lshl_add_u64 v[26:27], v[14:15], 0, v[20:21]
	global_load_dwordx4 v[76:79], v[24:25], off
	global_load_dwordx4 v[80:83], v[24:25], off offset:64
	global_load_dwordx4 v[68:71], v[24:25], off offset:128
	global_load_dwordx4 v[72:75], v[24:25], off offset:192
	v_lshl_add_u64 v[24:25], v[26:27], 0, v[0:1]
	v_and_b32_e32 v0, 0xf0, v7
	v_lshlrev_b32_e32 v33, 2, v8
	v_mov_b32_e32 v5, v1
	v_lshlrev_b32_e32 v162, 4, v30
	v_readlane_b32 s6, v217, 43
	v_lshlrev_b64 v[4:5], 9, v[4:5]
	v_add_u32_e32 v38, 0, v162
	v_lshlrev_b32_e32 v164, 4, v36
	v_readlane_b32 s7, v217, 44
	v_ashrrev_i32_e32 v8, 3, v30
	v_add_u32_e32 v39, 0, v164
	v_lshl_add_u64 v[16:17], s[6:7], 0, v[4:5]
	v_readfirstlane_b32 s6, v38
	v_lshl_add_u64 v[14:15], v[14:15], 0, v[22:23]
	v_ashrrev_i32_e32 v9, 31, v8
	v_readfirstlane_b32 s7, v39
	s_mov_b32 m0, s6
	v_lshl_add_u64 v[14:15], v[14:15], 0, v[0:1]
	v_and_b32_e32 v0, 0x70, v40
	s_barrier
	s_waitcnt vmcnt(6)
	v_mul_f32_e32 v3, v28, v29
	ds_bpermute_b32 v3, v135, v3
	s_waitcnt vmcnt(4)
	v_mul_f32_e32 v13, v31, v32
	ds_bpermute_b32 v13, v135, v13
	global_load_lds_dwordx4 v[24:25], off
	s_waitcnt lgkmcnt(0)
	v_fmac_f32_e32 v3, v28, v29
	ds_bpermute_b32 v7, v136, v3
	v_fmac_f32_e32 v13, v31, v32
	ds_bpermute_b32 v26, v136, v13
	s_mov_b32 m0, s7
	v_lshlrev_b64 v[8:9], 9, v[8:9]
	s_waitcnt lgkmcnt(0)
	v_add_f32_e32 v3, v3, v7
	global_load_lds_dwordx4 v[14:15], off
	v_add_f32_e32 v7, v13, v26
	ds_bpermute_b32 v13, v33, v3
	ds_bpermute_b32 v28, v33, v7
	v_lshl_add_u64 v[26:27], v[16:17], 0, v[0:1]
	v_lshl_add_u64 v[24:25], v[24:25], 0, s[46:47]
	v_lshl_add_u64 v[14:15], v[14:15], 0, s[46:47]
	s_waitcnt lgkmcnt(0)
	v_add_f32_e32 v3, v3, v13
	v_add_u32_e32 v13, 0x4000, v38
	v_add_f32_e32 v7, v7, v28
	v_readfirstlane_b32 s6, v13
	v_lshl_add_u64 v[28:29], v[26:27], 0, v[8:9]
	s_mov_b32 m0, s6
	v_add_u32_e32 v13, 0x4000, v39
	global_load_lds_dwordx4 v[28:29], off
	v_ashrrev_i32_e32 v28, 3, v36
	v_ashrrev_i32_e32 v29, 31, v28
	v_lshlrev_b64 v[28:29], 9, v[28:29]
	v_readfirstlane_b32 s6, v13
	v_add_u32_e32 v13, 0x8000, v38
	v_lshl_add_u64 v[26:27], v[26:27], 0, v[28:29]
	s_mov_b32 m0, s6
	v_readfirstlane_b32 s6, v13
	v_add_u32_e32 v13, 0x8000, v39
	global_load_lds_dwordx4 v[26:27], off
	s_mov_b32 m0, s6
	v_readfirstlane_b32 s6, v13
	global_load_lds_dwordx4 v[24:25], off
	s_mov_b32 m0, s6
	v_add_u32_e32 v13, 0xc000, v38
	global_load_lds_dwordx4 v[14:15], off
	v_lshl_add_u64 v[14:15], v[16:17], 0, v[8:9]
	v_lshl_add_u64 v[14:15], v[14:15], 0, v[0:1]
	v_readfirstlane_b32 s6, v13
	v_lshl_add_u64 v[14:15], v[14:15], 0, s[30:31]
	s_mov_b32 m0, s6
	ds_bpermute_b32 v13, v34, v7
	global_load_lds_dwordx4 v[14:15], off
	v_lshl_add_u64 v[14:15], v[16:17], 0, v[28:29]
	v_lshl_add_u64 v[14:15], v[14:15], 0, v[0:1]
	v_add_u32_e32 v0, 0xc000, v39
	v_lshl_add_u64 v[14:15], v[14:15], 0, s[30:31]
	v_readfirstlane_b32 s6, v0
	s_mov_b32 m0, s6
	ds_bpermute_b32 v0, v34, v3
	global_load_lds_dwordx4 v[14:15], off
	v_bfe_u32 v250, v142, 4, 2
	v_lshlrev_b32_e32 v250, 4, v250
	global_load_dwordx4 v[218:221], v250, s[92:93]
	global_load_dwordx4 v[222:225], v250, s[92:93] offset:64
	global_load_dwordx4 v[226:229], v250, s[92:93] offset:128
	global_load_dwordx4 v[230:233], v250, s[92:93] offset:192
	global_load_dwordx4 v[234:237], v250, s[92:93] offset:256
	global_load_dwordx4 v[238:241], v250, s[92:93] offset:320
	global_load_dwordx4 v[242:245], v250, s[92:93] offset:384
	global_load_dwordx4 v[246:249], v250, s[92:93] offset:448
	v_bfe_u32 v134, v30, 4, 2
	s_waitcnt lgkmcnt(0)
	v_add_f32_e32 v170, v7, v13
	v_add_f32_e32 v169, v3, v0
	v_lshl_add_u32 v3, v35, 8, 0
	v_bitop3_b32 v7, v134, v30, 15 bitop3:0x78
	v_cmp_lt_i32_e32 vcc, v153, v148
	v_lshl_add_u32 v167, v7, 4, v3
	v_bitop3_b32 v7, v134, v35, 4 bitop3:0x36
	v_cndmask_b32_e32 v0, v147, v153, vcc
	v_lshl_add_u32 v168, v7, 4, v3
	v_bitop3_b32 v7, v134, v35, 8 bitop3:0x36
	v_lshlrev_b32_e32 v0, 2, v0
	v_lshl_add_u32 v165, v7, 4, v3
	v_bitop3_b32 v7, v134, v35, 12 bitop3:0x36
	s_add_i32 s8, 0, 0x4000
	ds_bpermute_b32 v171, v0, v169
	ds_bpermute_b32 v172, v0, v170
	v_lshrrev_b32_e32 v0, 1, v30
	v_lshl_add_u32 v166, v7, 4, v3
	v_lshl_add_u32 v7, v35, 7, s8
	v_bfe_u32 v13, v30, 5, 1
	v_bfe_u32 v3, v30, 1, 3
	v_and_or_b32 v7, v0, 8, v7
	v_bitop3_b32 v0, v13, v0, 7 bitop3:0x78
	v_lshl_add_u32 v117, v0, 4, v7
	v_bitop3_b32 v0, v13, v3, 2 bitop3:0x36
	v_lshl_add_u32 v137, v0, 4, v7
	v_bitop3_b32 v0, v13, v3, 4 bitop3:0x36
	v_lshl_add_u32 v138, v0, 4, v7
	v_bitop3_b32 v0, v13, v3, 6 bitop3:0x36
	v_lshl_add_u32 v139, v0, 4, v7
	v_bitop3_b32 v0, v37, 7, v30 bitop3:0x48
	v_lshl_add_u64 v[14:15], v[28:29], 0, v[4:5]
	v_lshlrev_b32_e32 v0, 4, v0
	v_lshl_add_u64 v[4:5], v[8:9], 0, v[4:5]
	v_or_b32_e32 v14, v14, v0
	s_mov_b64 s[8:9], 0x8560100
	v_or_b32_e32 v4, v4, v0
	v_and_b32_e32 v0, 0xffffff00, v2
	v_lshl_add_u64 v[124:125], v[4:5], 0, s[8:9]
	v_lshl_add_u64 v[2:3], v[22:23], 0, v[0:1]
	v_bitop3_b32 v4, v12, 15, v30 bitop3:0x48
	v_lshl_or_b32 v2, v4, 4, v2
	v_lshl_add_u64 v[122:123], v[14:15], 0, s[8:9]
	v_lshl_add_u64 v[2:3], v[2:3], 0, v[10:11]
	s_mov_b64 s[8:9], 0x69a0000
	v_lshl_add_u64 v[126:127], v[2:3], 0, s[8:9]
	v_lshl_add_u64 v[2:3], v[20:21], 0, v[0:1]
	v_bitop3_b32 v0, v6, 15, v30 bitop3:0x48
	v_lshl_or_b32 v2, v0, 4, v2
	v_lshl_add_u64 v[2:3], v[2:3], 0, v[10:11]
	v_lshl_add_u64 v[128:129], v[2:3], 0, s[8:9]
	v_mov_b32_e32 v2, v1
	v_mov_b32_e32 v3, v1
	v_lshlrev_b64 v[120:121], 10, v[18:19]
	v_mov_b32_e32 v0, v1
	v_mov_b64_e32 v[6:7], v[2:3]
	v_mov_b64_e32 v[10:11], v[2:3]
	v_mov_b64_e32 v[18:19], v[2:3]
	v_mov_b64_e32 v[30:31], v[2:3]
	v_mov_b64_e32 v[38:39], v[2:3]
	v_mov_b64_e32 v[46:47], v[2:3]
	v_mov_b64_e32 v[54:55], v[2:3]
	v_mov_b64_e32 v[62:63], v[2:3]
	v_mov_b64_e32 v[66:67], v[2:3]
	v_mov_b64_e32 v[58:59], v[2:3]
	v_mov_b64_e32 v[50:51], v[2:3]
	v_mov_b64_e32 v[42:43], v[2:3]
	v_mov_b64_e32 v[34:35], v[2:3]
	v_mov_b64_e32 v[26:27], v[2:3]
	v_mov_b64_e32 v[22:23], v[2:3]
	v_mov_b64_e32 v[14:15], v[2:3]
	s_mov_b32 s6, 2
	s_mov_b32 s7, 0
	v_mov_b32_e32 v140, 0
	v_mov_b32_e32 v161, 0xf149f2ca
	v_mov_b64_e32 v[4:5], v[0:1]
	v_mov_b64_e32 v[8:9], v[0:1]
	v_mov_b64_e32 v[16:17], v[0:1]
	v_mov_b64_e32 v[28:29], v[0:1]
	v_mov_b64_e32 v[36:37], v[0:1]
	v_mov_b64_e32 v[44:45], v[0:1]
	v_mov_b64_e32 v[52:53], v[0:1]
	v_mov_b64_e32 v[60:61], v[0:1]
	v_mov_b32_e32 v163, 0xf149f2ca
	v_mov_b32_e32 v141, 0
	v_mov_b64_e32 v[64:65], v[0:1]
	v_mov_b64_e32 v[56:57], v[0:1]
	v_mov_b64_e32 v[48:49], v[0:1]
	v_mov_b64_e32 v[40:41], v[0:1]
	v_mov_b64_e32 v[32:33], v[0:1]
	v_mov_b64_e32 v[24:25], v[0:1]
	v_mov_b64_e32 v[20:21], v[0:1]
	v_mov_b64_e32 v[12:13], v[0:1]
	s_mov_b32 s8, 0
	s_waitcnt vmcnt(0)
	s_branch .LBB0_140

.LBB0_150:
	v_sub_f32_e32 v92, v92, v163
	v_sub_f32_e32 v93, v93, v163
	v_exp_f32_e32 v92, v92
	v_exp_f32_e32 v93, v93
	v_sub_f32_e32 v88, v88, v163
	v_sub_f32_e32 v94, v94, v163
	v_exp_f32_e32 v105, v88
	v_sub_f32_e32 v88, v89, v163
	v_exp_f32_e32 v94, v94
	v_sub_f32_e32 v95, v95, v163
	v_exp_f32_e32 v106, v88
	v_sub_f32_e32 v88, v90, v163
	v_exp_f32_e32 v95, v95
	v_exp_f32_e32 v107, v88
	v_sub_f32_e32 v88, v91, v163
	v_exp_f32_e32 v108, v88
	v_cvt_pk_bf16_f32 v88, v92, v93
	v_add_f32_e32 v92, 0, v92
	v_add_f32_e32 v92, v93, v92
	v_add_f32_e32 v92, v94, v92
	v_sub_f32_e32 v72, v100, v163
	v_add_f32_e32 v92, v95, v92
	v_exp_f32_e32 v100, v72
	v_sub_f32_e32 v72, v101, v163
	v_add_f32_e32 v92, v105, v92
	v_exp_f32_e32 v101, v72
	v_sub_f32_e32 v72, v102, v163
	v_add_f32_e32 v92, v106, v92
	v_exp_f32_e32 v102, v72
	v_sub_f32_e32 v72, v103, v163
	v_add_f32_e32 v92, v107, v92
	v_exp_f32_e32 v103, v72
	v_sub_f32_e32 v72, v96, v163
	v_add_f32_e32 v92, v108, v92
	v_exp_f32_e32 v96, v72
	v_sub_f32_e32 v72, v97, v163
	v_add_f32_e32 v92, v100, v92
	v_exp_f32_e32 v97, v72
	v_sub_f32_e32 v72, v98, v163
	v_add_f32_e32 v92, v101, v92
	v_exp_f32_e32 v98, v72
	v_sub_f32_e32 v72, v99, v163
	v_add_f32_e32 v92, v102, v92
	s_waitcnt lgkmcnt(0)
	v_add_f32_e32 v3, v3, v104
	v_add_f32_e32 v0, v0, v2
	v_exp_f32_e32 v99, v72
	v_add_f32_e32 v92, v103, v92
	v_mul_f32_e32 v3, 0x3fb8aa3b, v3
	v_mul_f32_e32 v0, 0x3fb8aa3b, v0
	v_add_f32_e32 v92, v96, v92
	v_exp_f32_e32 v3, v3
	v_exp_f32_e32 v0, v0
	v_add_f32_e32 v92, v97, v92
	v_add_f32_e32 v2, v98, v92
	v_add_f32_e32 v2, v99, v2
	v_cvt_pk_bf16_f32 v91, v107, v108
	v_add_f32_e32 v108, v141, v2
	v_sub_f32_e32 v2, v3, v0
	v_sub_f32_e32 v0, v84, v161
	v_exp_f32_e32 v0, v0
	v_sub_f32_e32 v3, v85, v161
	v_exp_f32_e32 v3, v3
	v_sub_f32_e32 v84, v86, v161
	v_exp_f32_e32 v84, v84
	v_sub_f32_e32 v85, v87, v161
	v_exp_f32_e32 v85, v85
	v_sub_f32_e32 v80, v80, v161
	v_add_f32_e32 v86, 0, v0
	v_exp_f32_e32 v80, v80
	v_sub_f32_e32 v81, v81, v161
	v_add_f32_e32 v86, v3, v86
	v_exp_f32_e32 v81, v81
	v_sub_f32_e32 v82, v82, v161
	v_add_f32_e32 v86, v84, v86
	v_exp_f32_e32 v82, v82
	v_sub_f32_e32 v83, v83, v161
	v_add_f32_e32 v86, v85, v86
	v_exp_f32_e32 v83, v83
	v_sub_f32_e32 v76, v76, v161
	v_add_f32_e32 v86, v80, v86
	v_exp_f32_e32 v76, v76
	v_sub_f32_e32 v77, v77, v161
	v_add_f32_e32 v86, v81, v86
	v_exp_f32_e32 v77, v77
	v_sub_f32_e32 v78, v78, v161
	v_add_f32_e32 v86, v82, v86
	v_exp_f32_e32 v78, v78
	v_sub_f32_e32 v79, v79, v161
	v_sub_f32_e32 v68, v68, v161
	v_add_f32_e32 v86, v83, v86
	v_exp_f32_e32 v79, v79
	v_exp_f32_e32 v87, v68
	v_sub_f32_e32 v68, v69, v161
	v_add_f32_e32 v86, v76, v86
	v_exp_f32_e32 v92, v68
	v_sub_f32_e32 v68, v70, v161
	v_add_f32_e32 v86, v77, v86
	v_exp_f32_e32 v93, v68
	v_sub_f32_e32 v68, v71, v161
	v_cvt_pk_bf16_f32 v89, v94, v95
	v_add_f32_e32 v86, v78, v86
	v_exp_f32_e32 v94, v68
	v_cvt_pk_bf16_f32 v70, v80, v81
	ds_read_b64 v[80:81], v117 offset:0
	v_add_f32_e32 v86, v79, v86
	v_cvt_pk_bf16_f32 v71, v82, v83
	ds_read_b64 v[82:83], v137 offset:0
	v_add_f32_e32 v68, v87, v86
	v_cvt_pk_bf16_f32 v69, v84, v85
	ds_read_b64 v[84:85], v138 offset:0
	v_add_f32_e32 v68, v92, v68
	v_cvt_pk_bf16_f32 v76, v76, v77
	v_cvt_pk_bf16_f32 v77, v78, v79
	v_cvt_pk_bf16_f32 v78, v87, v92
	ds_read_b64 v[86:87], v139 offset:0
	v_add_f32_e32 v68, v93, v68
	v_cvt_pk_bf16_f32 v79, v93, v94
	ds_read_b64 v[92:93], v117 offset:2048
	v_add_f32_e32 v68, v94, v68
	ds_read_b64 v[94:95], v137 offset:2048
	v_cvt_pk_bf16_f32 v74, v96, v97
	ds_read_b64 v[96:97], v138 offset:2048
	v_cvt_pk_bf16_f32 v75, v98, v99
	ds_read_b64 v[98:99], v139 offset:2048
	v_cvt_pk_bf16_f32 v72, v100, v101
	ds_read_b64 v[100:101], v117 offset:4096
	v_cvt_pk_bf16_f32 v73, v102, v103
	ds_read_b64 v[102:103], v137 offset:4096
	v_cvt_pk_bf16_f32 v90, v105, v106
	ds_read_b64 v[104:105], v138 offset:4096
	ds_read_b64 v[106:107], v139 offset:4096
	v_add_f32_e32 v109, v140, v68
	v_cvt_pk_bf16_f32 v68, v0, v3
	s_waitcnt lgkmcnt(8)
	v_mfma_f32_16x16x32_bf16 v[64:67], v[80:83], v[88:91], v[64:67]
	s_nop 0
	v_mfma_f32_16x16x32_bf16 v[80:83], v[80:83], v[68:71], v[60:63]
	v_mfma_f32_16x16x32_bf16 v[60:63], v[84:87], v[72:75], v[64:67]
	v_mfma_f32_16x16x32_bf16 v[64:67], v[84:87], v[76:79], v[80:83]
	ds_read_b64 v[80:81], v117 offset:6144
	ds_read_b64 v[82:83], v137 offset:6144
	ds_read_b64 v[84:85], v138 offset:6144
	ds_read_b64 v[86:87], v139 offset:6144
	s_waitcnt lgkmcnt(8)
	v_mfma_f32_16x16x32_bf16 v[56:59], v[92:95], v[88:91], v[56:59]
	v_mfma_f32_16x16x32_bf16 v[92:95], v[92:95], v[68:71], v[52:55]
	v_mfma_f32_16x16x32_bf16 v[52:55], v[96:99], v[72:75], v[56:59]
	v_mfma_f32_16x16x32_bf16 v[56:59], v[96:99], v[76:79], v[92:95]
	ds_read_b64 v[92:93], v117 offset:8192
	ds_read_b64 v[94:95], v137 offset:8192
	ds_read_b64 v[96:97], v138 offset:8192
	ds_read_b64 v[98:99], v139 offset:8192
	s_waitcnt lgkmcnt(8)
	v_mfma_f32_16x16x32_bf16 v[48:51], v[100:103], v[88:91], v[48:51]
	v_mfma_f32_16x16x32_bf16 v[100:103], v[100:103], v[68:71], v[44:47]
	v_mfma_f32_16x16x32_bf16 v[44:47], v[104:107], v[72:75], v[48:51]
	v_mfma_f32_16x16x32_bf16 v[48:51], v[104:107], v[76:79], v[100:103]
	ds_read_b64 v[100:101], v117 offset:10240
	ds_read_b64 v[102:103], v137 offset:10240
	ds_read_b64 v[104:105], v138 offset:10240
	ds_read_b64 v[106:107], v139 offset:10240
	s_waitcnt lgkmcnt(8)
	v_mfma_f32_16x16x32_bf16 v[40:43], v[80:83], v[88:91], v[40:43]
	v_mfma_f32_16x16x32_bf16 v[80:83], v[80:83], v[68:71], v[36:39]
	v_mfma_f32_16x16x32_bf16 v[36:39], v[84:87], v[72:75], v[40:43]
	v_mfma_f32_16x16x32_bf16 v[40:43], v[84:87], v[76:79], v[80:83]
	ds_read_b64 v[80:81], v117 offset:12288
	ds_read_b64 v[82:83], v137 offset:12288
	ds_read_b64 v[84:85], v138 offset:12288
	ds_read_b64 v[86:87], v139 offset:12288
	s_waitcnt lgkmcnt(8)
	v_mfma_f32_16x16x32_bf16 v[32:35], v[92:95], v[88:91], v[32:35]
	v_mfma_f32_16x16x32_bf16 v[92:95], v[92:95], v[68:71], v[28:31]
	v_mfma_f32_16x16x32_bf16 v[28:31], v[96:99], v[72:75], v[32:35]
	v_mfma_f32_16x16x32_bf16 v[32:35], v[96:99], v[76:79], v[92:95]
	ds_read_b64 v[92:93], v117 offset:14336
	ds_read_b64 v[94:95], v137 offset:14336
	ds_read_b64 v[96:97], v138 offset:14336
	ds_read_b64 v[98:99], v139 offset:14336
	s_waitcnt lgkmcnt(8)
	v_mfma_f32_16x16x32_bf16 v[24:27], v[100:103], v[88:91], v[24:27]
	v_mfma_f32_16x16x32_bf16 v[100:103], v[100:103], v[68:71], v[16:19]
	v_mfma_f32_16x16x32_bf16 v[16:19], v[104:107], v[72:75], v[24:27]
	v_mfma_f32_16x16x32_bf16 v[100:103], v[104:107], v[76:79], v[100:103]
	s_waitcnt lgkmcnt(4)
	v_mfma_f32_16x16x32_bf16 v[20:23], v[80:83], v[88:91], v[20:23]
	v_mfma_f32_16x16x32_bf16 v[24:27], v[80:83], v[68:71], v[8:11]
	v_mfma_f32_16x16x32_bf16 v[8:11], v[84:87], v[72:75], v[20:23]
	v_mfma_f32_16x16x32_bf16 v[80:83], v[84:87], v[76:79], v[24:27]
	s_waitcnt lgkmcnt(0)
	v_mfma_f32_16x16x32_bf16 v[12:15], v[92:95], v[88:91], v[12:15]
	v_mfma_f32_16x16x32_bf16 v[4:7], v[92:95], v[68:71], v[4:7]
	v_mfma_f32_16x16x32_bf16 v[68:71], v[96:99], v[72:75], v[12:15]
	v_mfma_f32_16x16x32_bf16 v[72:75], v[96:99], v[76:79], v[4:7]
	ds_bpermute_b32 v0, v136, v108
	s_waitcnt lgkmcnt(0)
	v_add_f32_e32 v0, v108, v0
	ds_bpermute_b32 v3, v135, v0
	s_waitcnt lgkmcnt(0)
	v_add_f32_e32 v0, v0, v3
	ds_bpermute_b32 v3, v136, v109
	v_div_scale_f32 v4, s[6:7], v0, v0, 1.0
	v_rcp_f32_e32 v5, v4
	s_waitcnt lgkmcnt(0)
	v_add_f32_e32 v3, v109, v3
	ds_bpermute_b32 v117, v135, v3
	v_fma_f32 v6, -v4, v5, 1.0
	v_fmac_f32_e32 v5, v6, v5
	v_div_scale_f32 v6, vcc, 1.0, v0, 1.0
	v_mul_f32_e32 v7, v6, v5
	v_fma_f32 v12, -v4, v7, v6
	v_fmac_f32_e32 v7, v12, v5
	v_fma_f32 v4, -v4, v7, v6
	s_waitcnt lgkmcnt(0)
	v_pk_add_f32 v[2:3], v[116:117], v[2:3]
	v_div_fmas_f32 v4, v4, v5, v7
	v_div_fixup_f32 v0, v4, v0, 1.0
	v_div_scale_f32 v4, s[6:7], v3, v3, v2
	v_rcp_f32_e32 v5, v4
	v_readlane_b32 s6, v217, 30
	v_readlane_b32 s7, v217, 31
	v_fma_f32 v6, -v4, v5, 1.0
	v_fmac_f32_e32 v5, v6, v5
	v_div_scale_f32 v6, vcc, v2, v3, v2
	v_mul_f32_e32 v7, v6, v5
	v_fma_f32 v12, -v4, v7, v6
	v_fmac_f32_e32 v7, v12, v5
	v_fma_f32 v4, -v4, v7, v6
	v_div_fmas_f32 v4, v4, v5, v7
	v_div_fixup_f32 v2, v4, v3, v2
	v_pk_mul_f32 v[4:5], v[64:65], v[2:3] op_sel_hi:[1,0]
	v_pk_mul_f32 v[6:7], v[66:67], v[2:3] op_sel_hi:[1,0]
	v_pk_fma_f32 v[12:13], v[60:61], v[0:1], v[4:5] op_sel_hi:[1,0,1] neg_lo:[0,0,1] neg_hi:[0,0,1]
	v_pk_fma_f32 v[6:7], v[62:63], v[0:1], v[6:7] op_sel_hi:[1,0,1] neg_lo:[0,0,1] neg_hi:[0,0,1]
	v_mul_f32_e32 v3, v13, v13
	v_fmac_f32_e32 v3, v12, v12
	v_fmac_f32_e32 v3, v6, v6
	v_fmac_f32_e32 v3, v7, v7
	v_pk_mul_f32 v[4:5], v[56:57], v[2:3] op_sel_hi:[1,0]
	v_pk_mul_f32 v[14:15], v[58:59], v[2:3] op_sel_hi:[1,0]
	v_pk_fma_f32 v[22:23], v[52:53], v[0:1], v[4:5] op_sel_hi:[1,0,1] neg_lo:[0,0,1] neg_hi:[0,0,1]
	v_pk_fma_f32 v[14:15], v[54:55], v[0:1], v[14:15] op_sel_hi:[1,0,1] neg_lo:[0,0,1] neg_hi:[0,0,1]
	v_mul_f32_e32 v4, v23, v23
	v_fmac_f32_e32 v4, v22, v22
	v_fmac_f32_e32 v4, v14, v14
	v_fmac_f32_e32 v4, v15, v15
	v_add_f32_e32 v3, v3, v4
	v_pk_mul_f32 v[4:5], v[48:49], v[2:3] op_sel_hi:[1,0]
	v_pk_mul_f32 v[20:21], v[50:51], v[2:3] op_sel_hi:[1,0]
	v_pk_fma_f32 v[44:45], v[44:45], v[0:1], v[4:5] op_sel_hi:[1,0,1] neg_lo:[0,0,1] neg_hi:[0,0,1]
	v_pk_mul_f32 v[4:5], v[40:41], v[2:3] op_sel_hi:[1,0]
	v_pk_fma_f32 v[26:27], v[46:47], v[0:1], v[20:21] op_sel_hi:[1,0,1] neg_lo:[0,0,1] neg_hi:[0,0,1]
	v_pk_fma_f32 v[24:25], v[36:37], v[0:1], v[4:5] op_sel_hi:[1,0,1] neg_lo:[0,0,1] neg_hi:[0,0,1]
	v_pk_mul_f32 v[20:21], v[42:43], v[2:3] op_sel_hi:[1,0]
	v_mov_b32_e32 v36, v25
	v_mov_b32_e32 v37, v45
	v_pk_fma_f32 v[20:21], v[38:39], v[0:1], v[20:21] op_sel_hi:[1,0,1] neg_lo:[0,0,1] neg_hi:[0,0,1]
	v_mov_b32_e32 v4, v24
	v_mov_b32_e32 v5, v44
	v_pk_mul_f32 v[36:37], v[36:37], v[36:37]
	s_nop 0
	v_pk_fma_f32 v[4:5], v[4:5], v[4:5], v[36:37]
	v_mov_b32_e32 v36, v20
	v_mov_b32_e32 v37, v26
	v_pk_fma_f32 v[4:5], v[36:37], v[36:37], v[4:5]
	v_mov_b32_e32 v36, v21
	v_mov_b32_e32 v37, v27
	v_pk_fma_f32 v[4:5], v[36:37], v[36:37], v[4:5]
	v_lshlrev_b32_e32 v37, 4, v134
	v_add_f32_e32 v3, v5, v3
	v_add_f32_e32 v3, v4, v3
	v_pk_mul_f32 v[4:5], v[32:33], v[2:3] op_sel_hi:[1,0]
	v_pk_mul_f32 v[32:33], v[34:35], v[2:3] op_sel_hi:[1,0]
	v_pk_fma_f32 v[34:35], v[28:29], v[0:1], v[4:5] op_sel_hi:[1,0,1] neg_lo:[0,0,1] neg_hi:[0,0,1]
	v_pk_mul_f32 v[4:5], v[100:101], v[2:3] op_sel_hi:[1,0]
	v_pk_mul_f32 v[28:29], v[102:103], v[2:3] op_sel_hi:[1,0]
	v_pk_fma_f32 v[16:17], v[16:17], v[0:1], v[4:5] op_sel_hi:[1,0,1] neg_lo:[0,0,1] neg_hi:[0,0,1]
	v_pk_fma_f32 v[18:19], v[18:19], v[0:1], v[28:29] op_sel_hi:[1,0,1] neg_lo:[0,0,1] neg_hi:[0,0,1]
	v_mov_b32_e32 v28, v17
	v_mov_b32_e32 v29, v35
	v_pk_fma_f32 v[30:31], v[30:31], v[0:1], v[32:33] op_sel_hi:[1,0,1] neg_lo:[0,0,1] neg_hi:[0,0,1]
	v_mov_b32_e32 v4, v16
	v_mov_b32_e32 v5, v34
	v_pk_mul_f32 v[28:29], v[28:29], v[28:29]
	s_nop 0
	v_pk_fma_f32 v[4:5], v[4:5], v[4:5], v[28:29]
	v_mov_b32_e32 v28, v18
	v_mov_b32_e32 v29, v30
	v_pk_fma_f32 v[4:5], v[28:29], v[28:29], v[4:5]
	v_mov_b32_e32 v28, v19
	v_mov_b32_e32 v29, v31
	v_pk_fma_f32 v[4:5], v[28:29], v[28:29], v[4:5]
	s_nop 0
	v_add_f32_e32 v3, v5, v3
	v_add_f32_e32 v36, v4, v3
	v_pk_mul_f32 v[4:5], v[80:81], v[2:3] op_sel_hi:[1,0]
	v_pk_mul_f32 v[28:29], v[82:83], v[2:3] op_sel_hi:[1,0]
	v_pk_fma_f32 v[32:33], v[8:9], v[0:1], v[4:5] op_sel_hi:[1,0,1] neg_lo:[0,0,1] neg_hi:[0,0,1]
	v_pk_mul_f32 v[4:5], v[72:73], v[2:3] op_sel_hi:[1,0]
	v_pk_fma_f32 v[28:29], v[10:11], v[0:1], v[28:29] op_sel_hi:[1,0,1] neg_lo:[0,0,1] neg_hi:[0,0,1]
	v_pk_fma_f32 v[10:11], v[68:69], v[0:1], v[4:5] op_sel_hi:[1,0,1] neg_lo:[0,0,1] neg_hi:[0,0,1]
	v_pk_mul_f32 v[2:3], v[74:75], v[2:3] op_sel_hi:[1,0]
	v_mov_b32_e32 v4, v11
	v_mov_b32_e32 v5, v33
	v_pk_fma_f32 v[8:9], v[70:71], v[0:1], v[2:3] op_sel_hi:[1,0,1] neg_lo:[0,0,1] neg_hi:[0,0,1]
	v_mov_b32_e32 v2, v10
	v_mov_b32_e32 v3, v32
	v_pk_mul_f32 v[4:5], v[4:5], v[4:5]
	s_nop 0
	v_pk_fma_f32 v[2:3], v[2:3], v[2:3], v[4:5]
	v_mov_b32_e32 v4, v8
	v_mov_b32_e32 v5, v28
	v_pk_fma_f32 v[2:3], v[4:5], v[4:5], v[2:3]
	v_mov_b32_e32 v4, v9
	v_mov_b32_e32 v5, v29
	v_pk_fma_f32 v[2:3], v[4:5], v[4:5], v[2:3]
	s_nop 0
	v_add_f32_e32 v0, v3, v36
	v_add_f32_e32 v0, v2, v0
	ds_bpermute_b32 v2, v136, v0
	s_waitcnt lgkmcnt(0)
	v_add_f32_e32 v0, v0, v2
	ds_bpermute_b32 v2, v135, v0
	s_waitcnt lgkmcnt(0)
	v_add_f32_e32 v0, v0, v2
	v_fmamk_f32 v0, v0, 0x3c000000, v144
	v_rsq_f32_e32 v0, v0
	v_lshl_add_u64 v[2:3], v[120:121], 1, s[6:7]
	v_mul_f32_e32 v36, v119, v0
	v_lshlrev_b32_e32 v0, 1, v118
	v_lshl_add_u64 v[2:3], v[2:3], 0, v[0:1]
	v_lshlrev_b32_e32 v0, 3, v134
	v_lshl_add_u64 v[38:39], v[2:3], 0, v[0:1]
	v_pk_mul_f32 v[12:13], v[12:13], v[36:37] op_sel_hi:[1,0]
	v_pk_mul_f32 v[6:7], v[6:7], v[36:37] op_sel_hi:[1,0]
	v_pk_mul_f32 v[8:9], v[8:9], v[36:37] op_sel_hi:[1,0]
	s_waitcnt vmcnt(0)
	v_pk_mul_f32 v[4:5], v[220:221], v[6:7]
	v_pk_mul_f32 v[2:3], v[218:219], v[12:13]
	v_pk_mul_f32 v[6:7], v[22:23], v[36:37] op_sel_hi:[1,0]
	v_cvt_pk_bf16_f32 v2, v2, v3
	v_cvt_pk_bf16_f32 v3, v4, v5
	global_store_dwordx2 v[38:39], v[2:3], off
	v_pk_mul_f32 v[12:13], v[14:15], v[36:37] op_sel_hi:[1,0]
	v_pk_mul_f32 v[2:3], v[222:223], v[6:7]
	v_pk_mul_f32 v[4:5], v[224:225], v[12:13]
	v_cvt_pk_bf16_f32 v2, v2, v3
	v_cvt_pk_bf16_f32 v3, v4, v5
	global_store_dwordx2 v[38:39], v[2:3], off offset:32
	v_pk_mul_f32 v[6:7], v[44:45], v[36:37] op_sel_hi:[1,0]
	v_pk_mul_f32 v[12:13], v[26:27], v[36:37] op_sel_hi:[1,0]
	v_pk_mul_f32 v[2:3], v[226:227], v[6:7]
	v_pk_mul_f32 v[4:5], v[228:229], v[12:13]
	v_cvt_pk_bf16_f32 v2, v2, v3
	v_cvt_pk_bf16_f32 v3, v4, v5
	global_store_dwordx2 v[38:39], v[2:3], off offset:64
	v_pk_mul_f32 v[6:7], v[24:25], v[36:37] op_sel_hi:[1,0]
	v_pk_mul_f32 v[12:13], v[20:21], v[36:37] op_sel_hi:[1,0]
	v_pk_mul_f32 v[2:3], v[230:231], v[6:7]
	v_pk_mul_f32 v[4:5], v[232:233], v[12:13]
	v_cvt_pk_bf16_f32 v2, v2, v3
	v_cvt_pk_bf16_f32 v3, v4, v5
	global_store_dwordx2 v[38:39], v[2:3], off offset:96
	v_pk_mul_f32 v[6:7], v[34:35], v[36:37] op_sel_hi:[1,0]
	v_pk_mul_f32 v[12:13], v[30:31], v[36:37] op_sel_hi:[1,0]
	v_pk_mul_f32 v[2:3], v[234:235], v[6:7]
	v_pk_mul_f32 v[4:5], v[236:237], v[12:13]
	v_cvt_pk_bf16_f32 v2, v2, v3
	v_cvt_pk_bf16_f32 v3, v4, v5
	global_store_dwordx2 v[38:39], v[2:3], off offset:128
	v_pk_mul_f32 v[6:7], v[16:17], v[36:37] op_sel_hi:[1,0]
	v_pk_mul_f32 v[12:13], v[18:19], v[36:37] op_sel_hi:[1,0]
	v_pk_mul_f32 v[2:3], v[238:239], v[6:7]
	v_pk_mul_f32 v[4:5], v[240:241], v[12:13]
	v_cvt_pk_bf16_f32 v2, v2, v3
	v_cvt_pk_bf16_f32 v3, v4, v5
	global_store_dwordx2 v[38:39], v[2:3], off offset:160
	v_pk_mul_f32 v[6:7], v[32:33], v[36:37] op_sel_hi:[1,0]
	v_pk_mul_f32 v[12:13], v[28:29], v[36:37] op_sel_hi:[1,0]
	v_pk_mul_f32 v[2:3], v[242:243], v[6:7]
	v_pk_mul_f32 v[4:5], v[244:245], v[12:13]
	v_cvt_pk_bf16_f32 v2, v2, v3
	v_cvt_pk_bf16_f32 v3, v4, v5
	global_store_dwordx2 v[38:39], v[2:3], off offset:192
	v_pk_mul_f32 v[6:7], v[10:11], v[36:37] op_sel_hi:[1,0]
	v_pk_mul_f32 v[4:5], v[248:249], v[8:9]
	v_pk_mul_f32 v[2:3], v[246:247], v[6:7]
	s_nop 0
	v_cvt_pk_bf16_f32 v2, v2, v3
	v_cvt_pk_bf16_f32 v3, v4, v5
	global_store_dwordx2 v[38:39], v[2:3], off offset:224

.LBB0_152:
	s_andn2_saveexec_b64 s[4:5], s[40:41]
	s_cbranch_execz .LBB0_115
	v_mov_b32_e32 v24, v142
	v_readlane_b32 s8, v217, 15
	v_and_b32_e32 v4, 63, v24
	v_lshlrev_b32_e32 v4, 2, v4
	global_load_dword v22, v4, s[42:43]
	global_load_dword v23, v4, s[42:43] offset:256
	global_load_dword v25, v4, s[42:43] offset:512
	global_load_dword v26, v4, s[42:43] offset:768
	v_cmp_lt_i32_e32 vcc, v149, v148
	v_readlane_b32 s9, v217, 16
	v_lshrrev_b32_e32 v27, 3, v0
	v_cndmask_b32_e32 v10, v147, v149, vcc
	v_cmp_lt_i32_e32 vcc, v150, v148
	v_lshlrev_b32_e32 v8, 7, v2
	v_mov_b64_e32 v[4:5], s[8:9]
	v_and_b32_e32 v9, 0xf8, v2
	v_readlane_b32 s8, v217, 11
	v_cndmask_b32_e32 v11, v147, v150, vcc
	v_cmp_lt_i32_e32 vcc, v151, v148
	v_readlane_b32 s9, v217, 12
	v_lshlrev_b32_e32 v14, 10, v27
	v_cndmask_b32_e32 v12, v147, v151, vcc
	v_cmp_lt_i32_e32 vcc, v152, v148
	v_and_b32_e32 v15, 0x380, v8
	v_or_b32_e32 v8, s19, v27
	v_add3_u32 v28, v9, s94, v3
	v_and_b32_e32 v31, 15, v24
	v_ashrrev_i32_e32 v9, 2, v24
	s_mov_b32 s12, 0x280000
	v_mov_b64_e32 v[6:7], s[8:9]
	v_cndmask_b32_e32 v13, v147, v152, vcc
	v_lshlrev_b32_e32 v136, 2, v11
	v_lshlrev_b32_e32 v29, 2, v12
	v_mad_i64_i32 v[4:5], s[8:9], v8, s12, v[4:5]
	v_ashrrev_i32_e32 v8, 4, v24
	v_add_u32_e32 v32, 0x200, v24
	v_and_b32_e32 v11, -16, v9
	v_or3_b32 v12, v15, v14, v31
	v_lshlrev_b32_e32 v135, 2, v10
	v_lshlrev_b32_e32 v30, 2, v13
	v_xor_b32_e32 v13, v8, v24
	v_ashrrev_i32_e32 v9, 31, v8
	v_ashrrev_i32_e32 v10, 4, v32
	v_add3_u32 v12, v11, v12, s88
	v_lshlrev_b64 v[14:15], 11, v[8:9]
	v_lshlrev_b32_e32 v9, 4, v13
	v_xor_b32_e32 v20, v10, v24
	v_ashrrev_i32_e32 v11, 31, v10
	v_ashrrev_i32_e32 v13, 31, v12
	v_readlane_b32 s10, v217, 45
	v_lshlrev_b64 v[18:19], 11, v[10:11]
	v_lshlrev_b32_e32 v11, 4, v20
	v_lshlrev_b64 v[20:21], 11, v[12:13]
	v_readlane_b32 s11, v217, 46
	v_lshlrev_b32_e32 v0, 8, v3
	v_lshl_add_u64 v[4:5], v[4:5], 0, v[0:1]
	v_lshl_add_u64 v[20:21], s[10:11], 0, v[20:21]
	v_lshl_add_u64 v[20:21], v[20:21], 0, v[0:1]
	v_and_b32_e32 v0, 48, v24
	v_lshl_add_u64 v[20:21], v[20:21], 0, v[0:1]
	v_and_b32_e32 v0, 0xf0, v9
	global_load_dwordx4 v[76:79], v[20:21], off
	global_load_dwordx4 v[80:83], v[20:21], off offset:64
	global_load_dwordx4 v[68:71], v[20:21], off offset:128
	global_load_dwordx4 v[72:75], v[20:21], off offset:192
	v_lshrrev_b32_e32 v33, 4, v24
	v_xor_b32_e32 v16, v33, v24
	v_lshlrev_b32_e32 v36, 4, v16
	v_lshl_add_u64 v[16:17], v[4:5], 0, v[14:15]
	v_lshl_add_u64 v[16:17], v[16:17], 0, v[0:1]
	v_and_b32_e32 v0, 0xf0, v11
	v_lshlrev_b32_e32 v162, 4, v24
	s_mov_b32 s13, 0x50000
	v_add_u32_e32 v34, 0, v162
	v_lshlrev_b32_e32 v164, 4, v32
	v_mad_i64_i32 v[6:7], s[8:9], v28, s13, v[6:7]
	v_readfirstlane_b32 s7, v34
	v_add_u32_e32 v35, 0, v164
	v_lshl_add_u64 v[4:5], v[4:5], 0, v[18:19]
	v_readfirstlane_b32 s8, v35
	s_mov_b32 m0, s7
	v_lshl_add_u64 v[4:5], v[4:5], 0, v[0:1]
	v_and_b32_e32 v0, 0x70, v36
	s_barrier
	s_waitcnt vmcnt(6)
	v_mul_f32_e32 v9, v22, v23
	ds_bpermute_b32 v9, v135, v9
	s_waitcnt vmcnt(4)
	v_mul_f32_e32 v20, v25, v26
	ds_bpermute_b32 v20, v135, v20
	global_load_lds_dwordx4 v[16:17], off
	s_waitcnt lgkmcnt(0)
	v_fmac_f32_e32 v9, v22, v23
	ds_bpermute_b32 v11, v136, v9
	v_fmac_f32_e32 v20, v25, v26
	ds_bpermute_b32 v21, v136, v20
	s_mov_b32 m0, s8
	s_movk_i32 s10, 0xa00
	s_waitcnt lgkmcnt(0)
	v_add_f32_e32 v9, v9, v11
	global_load_lds_dwordx4 v[4:5], off
	v_add_f32_e32 v11, v20, v21
	ds_bpermute_b32 v20, v29, v9
	ds_bpermute_b32 v21, v29, v11
	v_ashrrev_i32_e32 v29, 3, v24
	v_lshl_add_u64 v[16:17], v[16:17], 0, s[46:47]
	v_lshl_add_u64 v[4:5], v[4:5], 0, s[46:47]
	s_waitcnt lgkmcnt(0)
	v_add_f32_e32 v9, v9, v20
	v_add_f32_e32 v11, v11, v21
	ds_bpermute_b32 v25, v30, v9
	ds_bpermute_b32 v26, v30, v11
	v_add_u32_e32 v30, 0x4000, v34
	v_lshl_add_u64 v[20:21], v[6:7], 0, v[0:1]
	v_readfirstlane_b32 s7, v30
	v_mad_i64_i32 v[22:23], s[8:9], v29, s10, v[20:21]
	s_mov_b32 m0, s7
	v_bfe_u32 v134, v24, 4, 2
	global_load_lds_dwordx4 v[22:23], off
	v_add_u32_e32 v23, 0x4000, v35
	v_ashrrev_i32_e32 v22, 3, v32
	v_readfirstlane_b32 s7, v23
	v_mad_i64_i32 v[20:21], s[8:9], v22, s10, v[20:21]
	s_mov_b32 m0, s7
	v_lshlrev_b32_e32 v118, 7, v3
	global_load_lds_dwordx4 v[20:21], off
	v_add_u32_e32 v20, 0x8000, v34
	v_lshl_add_u32 v3, v31, 8, 0
	v_readfirstlane_b32 s7, v20
	s_mov_b32 m0, s7
	v_cmp_lt_i32_e32 vcc, v153, v148
	global_load_lds_dwordx4 v[16:17], off
	v_add_u32_e32 v16, 0x8000, v35
	s_waitcnt lgkmcnt(0)
	v_add_f32_e32 v165, v9, v25
	v_readfirstlane_b32 s7, v16
	s_mov_b32 m0, s7
	v_add_u32_e32 v16, 0xc000, v34
	global_load_lds_dwordx4 v[4:5], off
	v_mad_i64_i32 v[4:5], s[8:9], v29, s10, v[6:7]
	v_lshl_add_u64 v[4:5], v[4:5], 0, v[0:1]
	v_readfirstlane_b32 s7, v16
	v_lshl_add_u64 v[4:5], v[4:5], 0, s[30:31]
	s_mov_b32 m0, s7
	v_add_f32_e32 v169, v11, v26
	global_load_lds_dwordx4 v[4:5], off
	v_mad_i64_i32 v[4:5], s[8:9], v22, s10, v[6:7]
	v_lshl_add_u64 v[4:5], v[4:5], 0, v[0:1]
	v_add_u32_e32 v0, 0xc000, v35
	v_lshl_add_u64 v[4:5], v[4:5], 0, s[30:31]
	v_readfirstlane_b32 s7, v0
	s_mov_b32 m0, s7
	v_cndmask_b32_e32 v0, v147, v153, vcc
	global_load_lds_dwordx4 v[4:5], off
	v_bfe_u32 v250, v142, 4, 2
	v_lshlrev_b32_e32 v250, 4, v250
	global_load_dwordx4 v[218:221], v250, s[92:93]
	global_load_dwordx4 v[222:225], v250, s[92:93] offset:64
	global_load_dwordx4 v[226:229], v250, s[92:93] offset:128
	global_load_dwordx4 v[230:233], v250, s[92:93] offset:192
	global_load_dwordx4 v[234:237], v250, s[92:93] offset:256
	global_load_dwordx4 v[238:241], v250, s[92:93] offset:320
	global_load_dwordx4 v[242:245], v250, s[92:93] offset:384
	global_load_dwordx4 v[246:249], v250, s[92:93] offset:448
	v_bitop3_b32 v4, v134, v24, 15 bitop3:0x78
	v_lshl_add_u32 v166, v4, 4, v3
	v_bitop3_b32 v4, v134, v31, 4 bitop3:0x36
	v_lshl_add_u32 v167, v4, 4, v3
	v_bitop3_b32 v4, v134, v31, 8 bitop3:0x36
	v_lshlrev_b32_e32 v0, 2, v0
	v_lshl_add_u32 v168, v4, 4, v3
	v_bitop3_b32 v4, v134, v31, 12 bitop3:0x36
	s_add_i32 s8, 0, 0x4000
	ds_bpermute_b32 v170, v0, v165
	ds_bpermute_b32 v172, v0, v169
	v_lshrrev_b32_e32 v0, 1, v24
	v_lshl_add_u32 v171, v4, 4, v3
	v_lshl_add_u32 v4, v31, 7, s8
	v_bfe_u32 v5, v24, 5, 1
	v_bfe_u32 v3, v24, 1, 3
	v_and_or_b32 v4, v0, 8, v4
	v_bitop3_b32 v0, v5, v0, 7 bitop3:0x78
	v_lshl_add_u32 v117, v0, 4, v4
	v_bitop3_b32 v0, v5, v3, 2 bitop3:0x36
	v_lshl_add_u32 v137, v0, 4, v4
	v_bitop3_b32 v0, v5, v3, 4 bitop3:0x36
	v_lshl_add_u32 v138, v0, 4, v4
	v_bitop3_b32 v0, v5, v3, 6 bitop3:0x36
	v_lshl_add_u32 v139, v0, 4, v4
	v_mad_i64_i32 v[4:5], s[8:9], v28, s13, v[130:131]
	v_bitop3_b32 v0, v33, 7, v24 bitop3:0x48
	v_mad_i64_i32 v[122:123], s[8:9], v22, s10, v[4:5]
	v_lshlrev_b32_e32 v0, 4, v0
	v_mad_i64_i32 v[124:125], s[8:9], v29, s10, v[4:5]
	v_or_b32_e32 v122, v122, v0
	v_or_b32_e32 v124, v124, v0
	v_add_u32_e32 v0, s19, v27
	v_mad_i64_i32 v[4:5], s[8:9], v0, s12, v[132:133]
	v_lshl_add_u64 v[6:7], v[4:5], 0, v[14:15]
	v_and_b32_e32 v0, 0xffffff00, v2
	v_lshl_add_u64 v[126:127], v[6:7], 0, v[0:1]
	v_bitop3_b32 v2, v8, 15, v24 bitop3:0x48
	v_lshl_or_b32 v126, v2, 4, v126
	v_lshl_add_u64 v[2:3], v[4:5], 0, v[18:19]
	v_lshl_add_u64 v[128:129], v[2:3], 0, v[0:1]
	v_bitop3_b32 v0, v10, 15, v24 bitop3:0x48
	v_mov_b32_e32 v2, v1
	v_mov_b32_e32 v3, v1
	v_lshlrev_b64 v[120:121], 10, v[12:13]
	v_lshl_or_b32 v128, v0, 4, v128
	v_mov_b32_e32 v0, v1
	v_mov_b64_e32 v[6:7], v[2:3]
	v_mov_b64_e32 v[10:11], v[2:3]
	v_mov_b64_e32 v[18:19], v[2:3]
	v_mov_b64_e32 v[30:31], v[2:3]
	v_mov_b64_e32 v[38:39], v[2:3]
	v_mov_b64_e32 v[46:47], v[2:3]
	v_mov_b64_e32 v[54:55], v[2:3]
	v_mov_b64_e32 v[62:63], v[2:3]
	v_mov_b64_e32 v[66:67], v[2:3]
	v_mov_b64_e32 v[58:59], v[2:3]
	v_mov_b64_e32 v[50:51], v[2:3]
	v_mov_b64_e32 v[42:43], v[2:3]
	v_mov_b64_e32 v[34:35], v[2:3]
	v_mov_b64_e32 v[26:27], v[2:3]
	v_mov_b64_e32 v[22:23], v[2:3]
	v_mov_b64_e32 v[14:15], v[2:3]
	s_mov_b32 s6, 2
	s_mov_b32 s7, 0
	v_mov_b32_e32 v140, 0
	v_mov_b32_e32 v161, 0xf149f2ca
	v_mov_b64_e32 v[4:5], v[0:1]
	v_mov_b64_e32 v[8:9], v[0:1]
	v_mov_b64_e32 v[16:17], v[0:1]
	v_mov_b64_e32 v[28:29], v[0:1]
	v_mov_b64_e32 v[36:37], v[0:1]
	v_mov_b64_e32 v[44:45], v[0:1]
	v_mov_b64_e32 v[52:53], v[0:1]
	v_mov_b64_e32 v[60:61], v[0:1]
	v_mov_b32_e32 v163, 0xf149f2ca
	v_mov_b32_e32 v141, 0
	v_mov_b64_e32 v[64:65], v[0:1]
	v_mov_b64_e32 v[56:57], v[0:1]
	v_mov_b64_e32 v[48:49], v[0:1]
	v_mov_b64_e32 v[40:41], v[0:1]
	v_mov_b64_e32 v[32:33], v[0:1]
	v_mov_b64_e32 v[24:25], v[0:1]
	v_mov_b64_e32 v[20:21], v[0:1]
	v_mov_b64_e32 v[12:13], v[0:1]
	s_mov_b32 s8, 0
	s_waitcnt vmcnt(0)
	s_branch .LBB0_155
